# P1 rotary epilogue: step s+1 cos/sin loads issued before step s stores, waits relaxed to vmcnt(2); on top of early barrier invalidate, x-loop re-deal, tagged LN exchange
# speedup vs baseline: 1.0199x; 1.0014x over previous
.LBB0_176:
	s_and_b64 vcc, exec, s[8:9]
	s_cbranch_vccnz .Lrope_pf2
	v_or_b32_e32 v114, 16, v182
	v_lshlrev_b32_e32 v114, 6, v114
	v_mov_b32_e32 v115, v155
	v_lshl_add_u64 v[122:123], v[160:161], 0, v[114:115]
	v_lshl_add_u64 v[126:127], v[164:165], 0, v[114:115]
	global_load_dwordx4 v[118:121], v[122:123], off offset:16
	global_load_dwordx4 v[114:117], v[122:123], off
	global_load_dwordx4 v[122:125], v[126:127], off offset:16
	global_load_dwordx4 v[126:129], v[126:127], off

.LBB0_178:
	s_and_b64 vcc, exec, s[8:9]
	s_cbranch_vccnz .LBB0_180
	v_and_b32_e32 v132, 64, v180
	v_xor_b32_e32 v131, 32, v180
	v_add_u32_e32 v132, 64, v132
	v_cmp_lt_i32_e32 vcc, v131, v132
	v_mov_b32_e32 v142, v109
	s_waitcnt vmcnt(2)
	v_mov_b32_e32 v143, v125
	v_cndmask_b32_e32 v131, v180, v131, vcc
	v_lshlrev_b32_e32 v131, 2, v131
	ds_bpermute_b32 v132, v131, v111
	ds_bpermute_b32 v134, v131, v110
	ds_bpermute_b32 v135, v131, v113
	ds_bpermute_b32 v136, v131, v107
	ds_bpermute_b32 v138, v131, v106
	s_waitcnt lgkmcnt(4)
	v_cndmask_b32_e64 v133, v132, -v132, s[10:11]
	s_waitcnt lgkmcnt(3)
	v_cndmask_b32_e64 v132, v134, -v134, s[10:11]
	ds_bpermute_b32 v134, v131, v112
	ds_bpermute_b32 v139, v131, v108
	ds_bpermute_b32 v131, v131, v109
	v_mov_b32_e32 v140, v121
	s_waitcnt lgkmcnt(5)
	v_cndmask_b32_e64 v135, v135, -v135, s[10:11]
	s_waitcnt lgkmcnt(2)
	v_cndmask_b32_e64 v134, v134, -v134, s[10:11]
	v_cndmask_b32_e64 v137, v136, -v136, s[10:11]
	s_waitcnt lgkmcnt(0)
	v_cndmask_b32_e64 v141, v131, -v131, s[10:11]
	v_cndmask_b32_e64 v136, v138, -v138, s[10:11]
	v_cndmask_b32_e64 v138, v139, -v139, s[10:11]
	v_pk_mul_f32 v[140:141], v[142:143], v[140:141]
	v_pk_mul_f32 v[132:133], v[126:127], v[132:133]
	v_pk_mul_f32 v[134:135], v[128:129], v[134:135]
	v_pk_mul_f32 v[136:137], v[122:123], v[136:137]
	v_mul_f32_e32 v108, v108, v120
	v_mul_f32_e32 v138, v124, v138
	v_mov_b32_e32 v109, v140
	v_mov_b32_e32 v139, v141
	v_pk_fma_f32 v[110:111], v[110:111], v[114:115], v[132:133]
	v_pk_fma_f32 v[112:113], v[112:113], v[116:117], v[134:135]
	v_pk_fma_f32 v[106:107], v[106:107], v[118:119], v[136:137]
	v_pk_add_f32 v[108:109], v[108:109], v[138:139]
.LBB0_180:
	s_and_b64 vcc, exec, s[8:9]
	s_cbranch_vccnz .Lrope_pf3
	v_or_b32_e32 v114, 32, v182
	v_lshlrev_b32_e32 v114, 6, v114
	v_mov_b32_e32 v115, v155
	v_lshl_add_u64 v[122:123], v[160:161], 0, v[114:115]
	v_lshl_add_u64 v[126:127], v[164:165], 0, v[114:115]
	global_load_dwordx4 v[118:121], v[122:123], off offset:16
	global_load_dwordx4 v[114:117], v[122:123], off
	global_load_dwordx4 v[122:125], v[126:127], off offset:16
	global_load_dwordx4 v[126:129], v[126:127], off

.LBB0_182:
	s_and_b64 vcc, exec, s[8:9]
	s_cbranch_vccnz .LBB0_184
	v_and_b32_e32 v100, 64, v180
	v_xor_b32_e32 v99, 32, v180
	v_add_u32_e32 v100, 64, v100
	v_cmp_lt_i32_e32 vcc, v99, v100
	v_mov_b32_e32 v110, v93
	s_waitcnt vmcnt(2)
	v_mov_b32_e32 v111, v125
	v_cndmask_b32_e32 v99, v180, v99, vcc
	v_lshlrev_b32_e32 v99, 2, v99
	ds_bpermute_b32 v100, v99, v95
	ds_bpermute_b32 v102, v99, v94
	ds_bpermute_b32 v103, v99, v97
	ds_bpermute_b32 v104, v99, v91
	ds_bpermute_b32 v106, v99, v90
	s_waitcnt lgkmcnt(4)
	v_cndmask_b32_e64 v101, v100, -v100, s[10:11]
	s_waitcnt lgkmcnt(3)
	v_cndmask_b32_e64 v100, v102, -v102, s[10:11]
	ds_bpermute_b32 v102, v99, v96
	ds_bpermute_b32 v107, v99, v92
	ds_bpermute_b32 v99, v99, v93
	v_mov_b32_e32 v108, v121
	s_waitcnt lgkmcnt(5)
	v_cndmask_b32_e64 v103, v103, -v103, s[10:11]
	s_waitcnt lgkmcnt(2)
	v_cndmask_b32_e64 v102, v102, -v102, s[10:11]
	v_cndmask_b32_e64 v105, v104, -v104, s[10:11]
	s_waitcnt lgkmcnt(0)
	v_cndmask_b32_e64 v109, v99, -v99, s[10:11]
	v_cndmask_b32_e64 v104, v106, -v106, s[10:11]
	v_cndmask_b32_e64 v106, v107, -v107, s[10:11]
	v_pk_mul_f32 v[108:109], v[110:111], v[108:109]
	v_pk_mul_f32 v[100:101], v[126:127], v[100:101]
	v_pk_mul_f32 v[102:103], v[128:129], v[102:103]
	v_pk_mul_f32 v[104:105], v[122:123], v[104:105]
	v_mul_f32_e32 v92, v92, v120
	v_mul_f32_e32 v106, v124, v106
	v_mov_b32_e32 v93, v108
	v_mov_b32_e32 v107, v109
	v_pk_fma_f32 v[94:95], v[94:95], v[114:115], v[100:101]
	v_pk_fma_f32 v[96:97], v[96:97], v[116:117], v[102:103]
	v_pk_fma_f32 v[90:91], v[90:91], v[118:119], v[104:105]
	v_pk_add_f32 v[92:93], v[92:93], v[106:107]
.LBB0_184:
	s_and_b64 vcc, exec, s[8:9]
	s_cbranch_vccnz .Lrope_pf4
	v_or_b32_e32 v114, 48, v182
	v_lshlrev_b32_e32 v114, 6, v114
	v_mov_b32_e32 v115, v155
	v_lshl_add_u64 v[122:123], v[160:161], 0, v[114:115]
	v_lshl_add_u64 v[126:127], v[164:165], 0, v[114:115]
	global_load_dwordx4 v[118:121], v[122:123], off offset:16
	global_load_dwordx4 v[114:117], v[122:123], off
	global_load_dwordx4 v[122:125], v[126:127], off offset:16
	global_load_dwordx4 v[126:129], v[126:127], off

.LBB0_186:
	s_and_b64 vcc, exec, s[8:9]
	s_cbranch_vccnz .LBB0_188
	v_and_b32_e32 v84, 64, v180
	v_xor_b32_e32 v83, 32, v180
	v_add_u32_e32 v84, 64, v84
	v_cmp_lt_i32_e32 vcc, v83, v84
	v_mov_b32_e32 v94, v77
	s_waitcnt vmcnt(2)
	v_mov_b32_e32 v95, v125
	v_cndmask_b32_e32 v83, v180, v83, vcc
	v_lshlrev_b32_e32 v83, 2, v83
	ds_bpermute_b32 v84, v83, v79
	ds_bpermute_b32 v86, v83, v78
	ds_bpermute_b32 v87, v83, v81
	ds_bpermute_b32 v88, v83, v75
	ds_bpermute_b32 v90, v83, v74
	s_waitcnt lgkmcnt(4)
	v_cndmask_b32_e64 v85, v84, -v84, s[10:11]
	s_waitcnt lgkmcnt(3)
	v_cndmask_b32_e64 v84, v86, -v86, s[10:11]
	ds_bpermute_b32 v86, v83, v80
	ds_bpermute_b32 v91, v83, v76
	ds_bpermute_b32 v83, v83, v77
	v_mov_b32_e32 v92, v121
	s_waitcnt lgkmcnt(5)
	v_cndmask_b32_e64 v87, v87, -v87, s[10:11]
	s_waitcnt lgkmcnt(2)
	v_cndmask_b32_e64 v86, v86, -v86, s[10:11]
	v_cndmask_b32_e64 v89, v88, -v88, s[10:11]
	s_waitcnt lgkmcnt(0)
	v_cndmask_b32_e64 v93, v83, -v83, s[10:11]
	v_cndmask_b32_e64 v88, v90, -v90, s[10:11]
	v_cndmask_b32_e64 v90, v91, -v91, s[10:11]
	v_pk_mul_f32 v[92:93], v[94:95], v[92:93]
	v_pk_mul_f32 v[84:85], v[126:127], v[84:85]
	v_pk_mul_f32 v[86:87], v[128:129], v[86:87]
	v_pk_mul_f32 v[88:89], v[122:123], v[88:89]
	v_mul_f32_e32 v76, v76, v120
	v_mul_f32_e32 v90, v124, v90
	v_mov_b32_e32 v77, v92
	v_mov_b32_e32 v91, v93
	v_pk_fma_f32 v[78:79], v[78:79], v[114:115], v[84:85]
	v_pk_fma_f32 v[80:81], v[80:81], v[116:117], v[86:87]
	v_pk_fma_f32 v[74:75], v[74:75], v[118:119], v[88:89]
	v_pk_add_f32 v[76:77], v[76:77], v[90:91]
.LBB0_188:
	s_and_b64 vcc, exec, s[8:9]
	s_cbranch_vccnz .Lrope_pf5
	v_and_b32_e32 v114, 0xfcf, v174
	v_lshlrev_b32_e32 v114, 6, v114
	v_mov_b32_e32 v115, v155
	v_lshl_add_u64 v[122:123], v[160:161], 0, v[114:115]
	v_lshl_add_u64 v[126:127], v[164:165], 0, v[114:115]
	global_load_dwordx4 v[118:121], v[122:123], off offset:16
	global_load_dwordx4 v[114:117], v[122:123], off
	global_load_dwordx4 v[122:125], v[126:127], off offset:16
	global_load_dwordx4 v[126:129], v[126:127], off

.LBB0_190:
	s_and_b64 vcc, exec, s[8:9]
	s_cbranch_vccnz .LBB0_192
	v_and_b32_e32 v68, 64, v180
	v_xor_b32_e32 v67, 32, v180
	v_add_u32_e32 v68, 64, v68
	v_cmp_lt_i32_e32 vcc, v67, v68
	v_mov_b32_e32 v78, v61
	s_waitcnt vmcnt(2)
	v_mov_b32_e32 v79, v125
	v_cndmask_b32_e32 v67, v180, v67, vcc
	v_lshlrev_b32_e32 v67, 2, v67
	ds_bpermute_b32 v68, v67, v63
	ds_bpermute_b32 v70, v67, v62
	ds_bpermute_b32 v71, v67, v65
	ds_bpermute_b32 v72, v67, v59
	ds_bpermute_b32 v74, v67, v58
	s_waitcnt lgkmcnt(4)
	v_cndmask_b32_e64 v69, v68, -v68, s[10:11]
	s_waitcnt lgkmcnt(3)
	v_cndmask_b32_e64 v68, v70, -v70, s[10:11]
	ds_bpermute_b32 v70, v67, v64
	ds_bpermute_b32 v75, v67, v60
	ds_bpermute_b32 v67, v67, v61
	v_mov_b32_e32 v76, v121
	s_waitcnt lgkmcnt(5)
	v_cndmask_b32_e64 v71, v71, -v71, s[10:11]
	s_waitcnt lgkmcnt(2)
	v_cndmask_b32_e64 v70, v70, -v70, s[10:11]
	v_cndmask_b32_e64 v73, v72, -v72, s[10:11]
	s_waitcnt lgkmcnt(0)
	v_cndmask_b32_e64 v77, v67, -v67, s[10:11]
	v_cndmask_b32_e64 v72, v74, -v74, s[10:11]
	v_cndmask_b32_e64 v74, v75, -v75, s[10:11]
	v_pk_mul_f32 v[76:77], v[78:79], v[76:77]
	v_pk_mul_f32 v[68:69], v[126:127], v[68:69]
	v_pk_mul_f32 v[70:71], v[128:129], v[70:71]
	v_pk_mul_f32 v[72:73], v[122:123], v[72:73]
	v_mul_f32_e32 v60, v60, v120
	v_mul_f32_e32 v74, v124, v74
	v_mov_b32_e32 v61, v76
	v_mov_b32_e32 v75, v77
	v_pk_fma_f32 v[62:63], v[62:63], v[114:115], v[68:69]
	v_pk_fma_f32 v[64:65], v[64:65], v[116:117], v[70:71]
	v_pk_fma_f32 v[58:59], v[58:59], v[118:119], v[72:73]
	v_pk_add_f32 v[60:61], v[60:61], v[74:75]
.LBB0_192:
	s_and_b64 vcc, exec, s[8:9]
	s_cbranch_vccnz .Lrope_pf6
	v_or_b32_e32 v114, 16, v66
	v_lshlrev_b32_e32 v114, 6, v114
	v_mov_b32_e32 v115, v155
	v_lshl_add_u64 v[122:123], v[160:161], 0, v[114:115]
	v_lshl_add_u64 v[126:127], v[164:165], 0, v[114:115]
	global_load_dwordx4 v[118:121], v[122:123], off offset:16
	global_load_dwordx4 v[114:117], v[122:123], off
	global_load_dwordx4 v[122:125], v[126:127], off offset:16
	global_load_dwordx4 v[126:129], v[126:127], off

.LBB0_194:
	s_and_b64 vcc, exec, s[8:9]
	s_cbranch_vccnz .LBB0_196
	v_and_b32_e32 v52, 64, v180
	v_xor_b32_e32 v51, 32, v180
	v_add_u32_e32 v52, 64, v52
	v_cmp_lt_i32_e32 vcc, v51, v52
	v_mov_b32_e32 v62, v45
	s_waitcnt vmcnt(2)
	v_mov_b32_e32 v63, v125
	v_cndmask_b32_e32 v51, v180, v51, vcc
	v_lshlrev_b32_e32 v51, 2, v51
	ds_bpermute_b32 v52, v51, v47
	ds_bpermute_b32 v54, v51, v46
	ds_bpermute_b32 v55, v51, v49
	ds_bpermute_b32 v56, v51, v43
	ds_bpermute_b32 v58, v51, v42
	s_waitcnt lgkmcnt(4)
	v_cndmask_b32_e64 v53, v52, -v52, s[10:11]
	s_waitcnt lgkmcnt(3)
	v_cndmask_b32_e64 v52, v54, -v54, s[10:11]
	ds_bpermute_b32 v54, v51, v48
	ds_bpermute_b32 v59, v51, v44
	ds_bpermute_b32 v51, v51, v45
	v_mov_b32_e32 v60, v121
	s_waitcnt lgkmcnt(5)
	v_cndmask_b32_e64 v55, v55, -v55, s[10:11]
	s_waitcnt lgkmcnt(2)
	v_cndmask_b32_e64 v54, v54, -v54, s[10:11]
	v_cndmask_b32_e64 v57, v56, -v56, s[10:11]
	s_waitcnt lgkmcnt(0)
	v_cndmask_b32_e64 v61, v51, -v51, s[10:11]
	v_cndmask_b32_e64 v56, v58, -v58, s[10:11]
	v_cndmask_b32_e64 v58, v59, -v59, s[10:11]
	v_pk_mul_f32 v[60:61], v[62:63], v[60:61]
	v_pk_mul_f32 v[52:53], v[126:127], v[52:53]
	v_pk_mul_f32 v[54:55], v[128:129], v[54:55]
	v_pk_mul_f32 v[56:57], v[122:123], v[56:57]
	v_mul_f32_e32 v44, v44, v120
	v_mul_f32_e32 v58, v124, v58
	v_mov_b32_e32 v45, v60
	v_mov_b32_e32 v59, v61
	v_pk_fma_f32 v[46:47], v[46:47], v[114:115], v[52:53]
	v_pk_fma_f32 v[48:49], v[48:49], v[116:117], v[54:55]
	v_pk_fma_f32 v[42:43], v[42:43], v[118:119], v[56:57]
	v_pk_add_f32 v[44:45], v[44:45], v[58:59]
.LBB0_196:
	s_and_b64 vcc, exec, s[8:9]
	s_cbranch_vccnz .Lrope_pf7
	v_or_b32_e32 v114, 32, v66
	v_lshlrev_b32_e32 v114, 6, v114
	v_mov_b32_e32 v115, v155
	v_lshl_add_u64 v[122:123], v[160:161], 0, v[114:115]
	v_lshl_add_u64 v[126:127], v[164:165], 0, v[114:115]
	global_load_dwordx4 v[118:121], v[122:123], off offset:16
	global_load_dwordx4 v[114:117], v[122:123], off
	global_load_dwordx4 v[122:125], v[126:127], off offset:16
	global_load_dwordx4 v[126:129], v[126:127], off

.LBB0_198:
	s_and_b64 vcc, exec, s[8:9]
	s_cbranch_vccnz .LBB0_200
	v_and_b32_e32 v36, 64, v180
	v_xor_b32_e32 v35, 32, v180
	v_add_u32_e32 v36, 64, v36
	v_cmp_lt_i32_e32 vcc, v35, v36
	v_mov_b32_e32 v46, v29
	s_waitcnt vmcnt(2)
	v_mov_b32_e32 v47, v125
	v_cndmask_b32_e32 v35, v180, v35, vcc
	v_lshlrev_b32_e32 v35, 2, v35
	ds_bpermute_b32 v36, v35, v31
	ds_bpermute_b32 v38, v35, v30
	ds_bpermute_b32 v39, v35, v33
	ds_bpermute_b32 v40, v35, v27
	ds_bpermute_b32 v42, v35, v26
	s_waitcnt lgkmcnt(4)
	v_cndmask_b32_e64 v37, v36, -v36, s[10:11]
	s_waitcnt lgkmcnt(3)
	v_cndmask_b32_e64 v36, v38, -v38, s[10:11]
	ds_bpermute_b32 v38, v35, v32
	ds_bpermute_b32 v43, v35, v28
	ds_bpermute_b32 v35, v35, v29
	v_mov_b32_e32 v44, v121
	s_waitcnt lgkmcnt(5)
	v_cndmask_b32_e64 v39, v39, -v39, s[10:11]
	s_waitcnt lgkmcnt(2)
	v_cndmask_b32_e64 v38, v38, -v38, s[10:11]
	v_cndmask_b32_e64 v41, v40, -v40, s[10:11]
	s_waitcnt lgkmcnt(0)
	v_cndmask_b32_e64 v45, v35, -v35, s[10:11]
	v_cndmask_b32_e64 v40, v42, -v42, s[10:11]
	v_cndmask_b32_e64 v42, v43, -v43, s[10:11]
	v_pk_mul_f32 v[44:45], v[46:47], v[44:45]
	v_pk_mul_f32 v[36:37], v[126:127], v[36:37]
	v_pk_mul_f32 v[38:39], v[128:129], v[38:39]
	v_pk_mul_f32 v[40:41], v[122:123], v[40:41]
	v_mul_f32_e32 v28, v28, v120
	v_mul_f32_e32 v42, v124, v42
	v_mov_b32_e32 v29, v44
	v_mov_b32_e32 v43, v45
	v_pk_fma_f32 v[30:31], v[30:31], v[114:115], v[36:37]
	v_pk_fma_f32 v[32:33], v[32:33], v[116:117], v[38:39]
	v_pk_fma_f32 v[26:27], v[26:27], v[118:119], v[40:41]
	v_pk_add_f32 v[28:29], v[28:29], v[42:43]
.LBB0_200:
	s_and_b64 vcc, exec, s[8:9]
	s_cbranch_vccnz .Lrope_pf8
	v_or_b32_e32 v114, 48, v66
	v_lshlrev_b32_e32 v114, 6, v114
	v_mov_b32_e32 v115, v155
	v_lshl_add_u64 v[122:123], v[160:161], 0, v[114:115]
	v_lshl_add_u64 v[126:127], v[164:165], 0, v[114:115]
	global_load_dwordx4 v[118:121], v[122:123], off offset:16
	global_load_dwordx4 v[114:117], v[122:123], off
	global_load_dwordx4 v[122:125], v[126:127], off offset:16
	global_load_dwordx4 v[126:129], v[126:127], off

.LBB0_202:
	s_and_b64 vcc, exec, s[8:9]
	s_cbranch_vccnz .LBB0_204
	v_and_b32_e32 v20, 64, v180
	v_xor_b32_e32 v19, 32, v180
	v_add_u32_e32 v20, 64, v20
	v_cmp_lt_i32_e32 vcc, v19, v20
	s_waitcnt vmcnt(2)
	v_mov_b32_e32 v28, v121
	v_cndmask_b32_e32 v19, v180, v19, vcc
	v_lshlrev_b32_e32 v19, 2, v19
	ds_bpermute_b32 v20, v19, v15
	ds_bpermute_b32 v22, v19, v14
	ds_bpermute_b32 v24, v19, v11
	ds_bpermute_b32 v26, v19, v10
	ds_bpermute_b32 v27, v19, v12
	ds_bpermute_b32 v23, v19, v17
	s_waitcnt lgkmcnt(5)
	v_cndmask_b32_e64 v21, v20, -v20, s[10:11]
	s_waitcnt lgkmcnt(4)
	v_cndmask_b32_e64 v20, v22, -v22, s[10:11]
	ds_bpermute_b32 v22, v19, v16
	ds_bpermute_b32 v19, v19, v13
	s_waitcnt lgkmcnt(5)
	v_cndmask_b32_e64 v25, v24, -v24, s[10:11]
	s_waitcnt lgkmcnt(4)
	v_cndmask_b32_e64 v24, v26, -v26, s[10:11]
	s_waitcnt lgkmcnt(3)
	v_cndmask_b32_e64 v26, v27, -v27, s[10:11]
	v_mul_f32_e32 v26, v124, v26
	s_waitcnt lgkmcnt(0)
	v_cndmask_b32_e64 v29, v19, -v19, s[10:11]
	v_mov_b32_e32 v124, v13
	v_cndmask_b32_e64 v23, v23, -v23, s[10:11]
	v_cndmask_b32_e64 v22, v22, -v22, s[10:11]
	v_pk_mul_f32 v[28:29], v[124:125], v[28:29]
	v_pk_mul_f32 v[20:21], v[126:127], v[20:21]
	v_pk_mul_f32 v[22:23], v[128:129], v[22:23]
	v_pk_mul_f32 v[24:25], v[122:123], v[24:25]
	v_mul_f32_e32 v12, v12, v120
	v_mov_b32_e32 v13, v28
	v_mov_b32_e32 v27, v29
	v_pk_fma_f32 v[14:15], v[14:15], v[114:115], v[20:21]
	v_pk_fma_f32 v[16:17], v[16:17], v[116:117], v[22:23]
	v_pk_fma_f32 v[10:11], v[10:11], v[118:119], v[24:25]
	v_pk_add_f32 v[12:13], v[12:13], v[26:27]
